# gemm_tile<4> K-loops (E1/O1): the three 64-bit DMA address adds moved from the loop head (before the stage wait + barrier) to behind the 16 fragment ds_reads
# speedup vs baseline: 1.0070x; 1.0070x over previous
; DI int get_bid() { int b = blockIdx.x; asm volatile("" : "+s"(b)); return b; }
; template <int MT, class Epi>
; DI void gemm_tile(const u16* __restrict__ X, long ldx, const u16* __restrict__ W, long ldw, int K, char* smem,
;                   int m0, int n0, const Epi& epi, bool pre = false, const u16* Xn = nullptr, const u16* Wn = nullptr) {
;     ...
;   do {
;     asm volatile("s_waitcnt vmcnt(0)" ::: "memory");
;     __syncthreads();
;     if (kt + 1 < nk) GT_DMA((unsigned)((kt + 1) & 1) * 32768u)
;     else if (Xn != nullptr) { xe = Xn + oxe; xo = Xn + oxo; we = Wn + owe; wo = Wn + owo; GT_DMA(0u) }
;     const char* cur = smem + (kt & 1) * 32768;
; #pragma unroll
;     for (int ks = 0; ks < 2; ++ks) {
;       bf16x8 xf[MT], wf[4];
;       const int ch = ((ks * 4 + g) ^ rsw) << 4;
; #pragma unroll
;       for (int i = 0; i < MT; ++i) xf[i] = *(const bf16x8*)(cur + (wm * 16 * MT + i * 16 + lr) * 128 + ch);
; #pragma unroll
;       for (int i = 0; i < 4; ++i) wf[i] = *(const bf16x8*)(cur + 16384 + (wn * 64 + i * 16 + lr) * 128 + ch);
; #pragma unroll
;       for (int nt = 0; nt < 4; ++nt)
; #pragma unroll
;         for (int mt = 0; mt < MT; ++mt)
;           acc[nt][mt] = __builtin_amdgcn_mfma_f32_16x16x32_bf16(wf[nt], xf[mt], acc[nt][mt], 0, 0, 0);
;     }
;   } while (++kt < nk);
; DI void phase_odd(const Params& p, int o, int sub, char* smem) {
;     ...
;     for (int t = get_bid(); t < 132 * 14; t += gridDim.x) {
;       const int tm = t / 14, tn = t % 14;
;       const int t2 = t + gridDim.x, tm2 = t2 / 14, tn2 = t2 % 14;
;       const bool nx = t2 < 132 * 14;
;       gemm_tile<4>(hbuf + (size_t)tm * 128 * 1024, 1024, W + WO_IN + (size_t)tn * 128 * 1024, 1024, 1024, smem, tm * 128, tn * 128, epi, pre,
;                    nx ? hbuf + (size_t)tm2 * 128 * 1024 : nullptr, W + WO_IN + (size_t)tn2 * 128 * 1024);
;       pre = nx;
.LBB0_144:
	s_add_i32 s7, s8, 0x8000
	s_and_b32 s9, s7, 0x8000
	s_waitcnt vmcnt(0)
	s_barrier
	s_and_b32 s8, s8, 0x8000
	v_or_b32_e32 v162, s8, v85
	v_add3_u32 v163, v162, v81, v82
	v_add3_u32 v164, v162, v84, v82
	v_or_b32_e32 v165, s8, v83
	v_add3_u32 v166, v165, v81, v82
	v_add3_u32 v167, v165, v84, v82
	ds_read_b128 v[86:89], v163
	ds_read_b128 v[90:93], v163 offset:2048
	ds_read_b128 v[94:97], v163 offset:4096
	ds_read_b128 v[98:101], v163 offset:6144
	ds_read_b128 v[102:105], v164 offset:16384
	ds_read_b128 v[106:109], v164 offset:18432
	ds_read_b128 v[110:113], v164 offset:20480
	ds_read_b128 v[114:117], v164 offset:22528
	ds_read_b128 v[130:133], v166
	ds_read_b128 v[134:137], v166 offset:2048
	ds_read_b128 v[138:141], v166 offset:4096
	ds_read_b128 v[142:145], v166 offset:6144
	ds_read_b128 v[146:149], v167 offset:16384
	ds_read_b128 v[150:153], v167 offset:18432
	ds_read_b128 v[154:157], v167 offset:20480
	ds_read_b128 v[158:161], v167 offset:22528
	v_lshl_add_u64 v[124:125], v[76:77], 0, s[40:41]
	v_lshl_add_u64 v[122:123], v[74:75], 0, s[40:41]
	v_lshl_add_u64 v[126:127], v[124:125], 0, s[74:75]
	s_add_i32 s10, s9, s5
	s_mov_b32 m0, s10
	s_nop 0
	global_load_lds_dwordx4 v[126:127], off
	v_lshl_add_u64 v[126:127], v[122:123], 0, s[94:95]
	s_add_i32 s11, s10, 0x400
	s_mov_b32 m0, s11
	s_nop 0
	global_load_lds_dwordx4 v[126:127], off
	v_lshl_add_u64 v[124:125], v[124:125], 0, s[76:77]
	s_add_i32 s11, s10, 0x800
	s_mov_b32 m0, s11
	s_nop 0
	global_load_lds_dwordx4 v[124:125], off
	v_lshl_add_u64 v[120:121], v[72:73], 0, s[40:41]
	v_lshl_add_u64 v[122:123], v[122:123], 0, s[54:55]
	s_addk_i32 s10, 0xc00
	s_mov_b32 m0, s10
	s_nop 0
	global_load_lds_dwordx4 v[122:123], off
	v_lshl_add_u64 v[118:119], v[70:71], 0, s[40:41]
	v_lshl_add_u64 v[128:129], v[120:121], 0, s[28:29]
	s_add_i32 s9, s9, s6
	s_mov_b32 m0, s9
	s_nop 0
	global_load_lds_dwordx4 v[128:129], off
	v_lshl_add_u64 v[122:123], v[118:119], 0, s[94:95]
	s_add_i32 s10, s9, 0x400
	s_mov_b32 m0, s10
	s_nop 0
	global_load_lds_dwordx4 v[122:123], off
	v_lshl_add_u64 v[120:121], v[120:121], 0, s[78:79]
	s_add_i32 s10, s9, 0x800
	s_mov_b32 m0, s10
	s_nop 0
	global_load_lds_dwordx4 v[120:121], off
	v_lshl_add_u64 v[118:119], v[118:119], 0, s[54:55]
	s_addk_i32 s9, 0xc00
	s_mov_b32 m0, s9
	s_nop 0
	global_load_lds_dwordx4 v[118:119], off
	s_mov_b32 s8, s7
	s_add_u32 s40, s40, 0x80
	s_addc_u32 s41, s41, 0
	s_cmpk_lg_i32 s40, 0x780
	s_waitcnt lgkmcnt(11)
	v_mfma_f32_16x16x32_bf16 v[62:65], v[102:105], v[86:89], v[62:65]
	v_mfma_f32_16x16x32_bf16 v[58:61], v[102:105], v[90:93], v[58:61]
	v_mfma_f32_16x16x32_bf16 v[54:57], v[102:105], v[94:97], v[54:57]
	v_mfma_f32_16x16x32_bf16 v[50:53], v[102:105], v[98:101], v[50:53]
	s_waitcnt lgkmcnt(10)
	v_mfma_f32_16x16x32_bf16 v[34:37], v[106:109], v[98:101], v[34:37]
	s_waitcnt lgkmcnt(9)
	v_mfma_f32_16x16x32_bf16 v[18:21], v[110:113], v[98:101], v[18:21]
	s_waitcnt lgkmcnt(8)
	v_mfma_f32_16x16x32_bf16 v[14:17], v[114:117], v[86:89], v[14:17]
	v_mfma_f32_16x16x32_bf16 v[10:13], v[114:117], v[90:93], v[10:13]
	v_mfma_f32_16x16x32_bf16 v[6:9], v[114:117], v[94:97], v[6:9]
	v_mfma_f32_16x16x32_bf16 v[2:5], v[114:117], v[98:101], v[2:5]
	v_mfma_f32_16x16x32_bf16 v[46:49], v[106:109], v[86:89], v[46:49]
	v_mfma_f32_16x16x32_bf16 v[42:45], v[106:109], v[90:93], v[42:45]
	v_mfma_f32_16x16x32_bf16 v[38:41], v[106:109], v[94:97], v[38:41]
	v_mfma_f32_16x16x32_bf16 v[30:33], v[110:113], v[86:89], v[30:33]
	v_mfma_f32_16x16x32_bf16 v[26:29], v[110:113], v[90:93], v[26:29]
	v_mfma_f32_16x16x32_bf16 v[22:25], v[110:113], v[94:97], v[22:25]
	s_waitcnt lgkmcnt(3)
	v_mfma_f32_16x16x32_bf16 v[62:65], v[146:149], v[130:133], v[62:65]
	v_mfma_f32_16x16x32_bf16 v[58:61], v[146:149], v[134:137], v[58:61]
	v_mfma_f32_16x16x32_bf16 v[54:57], v[146:149], v[138:141], v[54:57]
	v_mfma_f32_16x16x32_bf16 v[50:53], v[146:149], v[142:145], v[50:53]
	s_waitcnt lgkmcnt(2)
	v_mfma_f32_16x16x32_bf16 v[46:49], v[150:153], v[130:133], v[46:49]
	v_mfma_f32_16x16x32_bf16 v[42:45], v[150:153], v[134:137], v[42:45]
	v_mfma_f32_16x16x32_bf16 v[38:41], v[150:153], v[138:141], v[38:41]
	v_mfma_f32_16x16x32_bf16 v[34:37], v[150:153], v[142:145], v[34:37]
	s_waitcnt lgkmcnt(1)
	v_mfma_f32_16x16x32_bf16 v[30:33], v[154:157], v[130:133], v[30:33]
	v_mfma_f32_16x16x32_bf16 v[26:29], v[154:157], v[134:137], v[26:29]
	v_mfma_f32_16x16x32_bf16 v[22:25], v[154:157], v[138:141], v[22:25]
	v_mfma_f32_16x16x32_bf16 v[18:21], v[154:157], v[142:145], v[18:21]
	s_waitcnt lgkmcnt(0)
	v_mfma_f32_16x16x32_bf16 v[14:17], v[158:161], v[130:133], v[14:17]
	v_mfma_f32_16x16x32_bf16 v[10:13], v[158:161], v[134:137], v[10:13]
	v_mfma_f32_16x16x32_bf16 v[6:9], v[158:161], v[138:141], v[6:9]
	v_mfma_f32_16x16x32_bf16 v[2:5], v[158:161], v[142:145], v[2:5]
	s_cbranch_scc1 .LBB0_144
	v_readlane_b32 s8, v255, 5
	v_readlane_b32 s14, v255, 11
	s_add_i32 s4, s4, s14
	s_mul_hi_i32 s7, s4, 0x92492493
	s_add_i32 s7, s7, s4
	s_lshr_b32 s8, s7, 31
	s_ashr_i32 s7, s7, 3
	s_add_i32 s46, s7, s8
	s_cmpk_gt_i32 s4, 0x737
	v_readlane_b32 s9, v255, 6
	s_cselect_b64 s[40:41], -1, 0
	s_ashr_i32 s47, s46, 31
	s_lshl_b64 s[8:9], s[46:47], 18
	s_add_u32 s7, s0, s8
	s_addc_u32 s8, s1, s9
	s_cmpk_lt_i32 s4, 0x738
	s_waitcnt vmcnt(0)
	s_cselect_b32 s45, s8, 0
	s_cselect_b32 s44, s7, 0
	v_readlane_b32 s12, v255, 9
	v_readlane_b32 s13, v255, 10
	s_cmp_eq_u64 s[44:45], 0
	v_readlane_b32 s10, v255, 7
	v_readlane_b32 s11, v255, 8
	v_readlane_b32 s15, v255, 12
	s_barrier
	s_cbranch_scc1 .LBB0_147
	s_mul_i32 s7, s46, 14
	s_sub_i32 s8, s4, s7
	s_ashr_i32 s9, s8, 31
	s_lshl_b64 s[8:9], s[8:9], 18
	s_add_u32 s8, s12, s8
	s_addc_u32 s9, s13, s9
	v_lshl_add_u64 v[70:71], s[44:45], 0, v[68:69]
	v_lshl_add_u64 v[72:73], s[8:9], 0, v[66:67]
	v_lshl_add_u64 v[66:67], s[44:45], 0, v[66:67]
	s_mov_b32 m0, s5
	s_nop 0
	global_load_lds_dwordx4 v[70:71], off
	s_mov_b64 s[10:11], 0x4000
	v_lshl_add_u64 v[68:69], s[8:9], 0, v[68:69]
	v_lshl_add_u64 v[74:75], v[66:67], 0, s[10:11]
	s_add_i32 s7, s5, 0x400
	s_mov_b32 m0, s7
	s_nop 0
	global_load_lds_dwordx4 v[74:75], off
	s_mov_b64 s[12:13], 0x8000
	v_lshl_add_u64 v[70:71], v[70:71], 0, s[12:13]
	s_add_i32 s7, s5, 0x800
	s_mov_b32 m0, s7
	s_nop 0
	global_load_lds_dwordx4 v[70:71], off
	s_mov_b64 s[14:15], 0xc000
	v_lshl_add_u64 v[66:67], v[66:67], 0, s[14:15]
	s_add_i32 s7, s5, 0xc00
	s_mov_b32 m0, s7
	s_nop 0
	global_load_lds_dwordx4 v[66:67], off
	s_mov_b32 m0, s6
	s_nop 0
	global_load_lds_dwordx4 v[68:69], off
	v_lshl_add_u64 v[66:67], v[72:73], 0, s[10:11]
	s_add_i32 s6, s5, 0x4400
	s_mov_b32 m0, s6
	s_nop 0
	global_load_lds_dwordx4 v[66:67], off
	v_lshl_add_u64 v[66:67], v[68:69], 0, s[12:13]
	s_add_i32 s6, s5, 0x4800
	s_mov_b32 m0, s6
	s_nop 0
	global_load_lds_dwordx4 v[66:67], off
	v_lshl_add_u64 v[66:67], v[72:73], 0, s[14:15]
	s_addk_i32 s5, 0x4c00
	s_mov_b32 m0, s5
	s_nop 0
	global_load_lds_dwordx4 v[66:67], off

; template <int MT, class Epi>
; DI void gemm_tile(const u16* __restrict__ X, long ldx, const u16* __restrict__ W, long ldw, int K, char* smem,
;                   int m0, int n0, const Epi& epi, bool pre = false, const u16* Xn = nullptr, const u16* Wn = nullptr) {
;     ...
;   do {
;     asm volatile("s_waitcnt vmcnt(0)" ::: "memory");
;     __syncthreads();
;     if (kt + 1 < nk) GT_DMA((unsigned)((kt + 1) & 1) * 32768u)
;     else if (Xn != nullptr) { xe = Xn + oxe; xo = Xn + oxo; we = Wn + owe; wo = Wn + owo; GT_DMA(0u) }
;     const char* cur = smem + (kt & 1) * 32768;
; #pragma unroll
;     for (int ks = 0; ks < 2; ++ks) {
;       bf16x8 xf[MT], wf[4];
;       const int ch = ((ks * 4 + g) ^ rsw) << 4;
; #pragma unroll
;       for (int i = 0; i < MT; ++i) xf[i] = *(const bf16x8*)(cur + (wm * 16 * MT + i * 16 + lr) * 128 + ch);
; #pragma unroll
;       for (int i = 0; i < 4; ++i) wf[i] = *(const bf16x8*)(cur + 16384 + (wn * 64 + i * 16 + lr) * 128 + ch);
; #pragma unroll
;       for (int nt = 0; nt < 4; ++nt)
; #pragma unroll
;         for (int mt = 0; mt < MT; ++mt)
;           acc[nt][mt] = __builtin_amdgcn_mfma_f32_16x16x32_bf16(wf[nt], xf[mt], acc[nt][mt], 0, 0, 0);
;     }
;   } while (++kt < nk);
.LBB0_422:
	s_add_i32 s7, s8, 0x8000
	s_and_b32 s9, s7, 0x8000
	s_waitcnt vmcnt(0)
	s_barrier
	s_and_b32 s8, s8, 0x8000
	v_or_b32_e32 v162, s8, v85
	v_add3_u32 v163, v162, v81, v82
	v_add3_u32 v164, v162, v84, v82
	v_or_b32_e32 v165, s8, v83
	v_add3_u32 v166, v165, v81, v82
	v_add3_u32 v167, v165, v84, v82
	ds_read_b128 v[86:89], v163
	ds_read_b128 v[90:93], v163 offset:2048
	ds_read_b128 v[94:97], v163 offset:4096
	ds_read_b128 v[98:101], v163 offset:6144
	ds_read_b128 v[102:105], v164 offset:16384
	ds_read_b128 v[106:109], v164 offset:18432
	ds_read_b128 v[110:113], v164 offset:20480
	ds_read_b128 v[114:117], v164 offset:22528
	ds_read_b128 v[130:133], v166
	ds_read_b128 v[134:137], v166 offset:2048
	ds_read_b128 v[138:141], v166 offset:4096
	ds_read_b128 v[142:145], v166 offset:6144
	ds_read_b128 v[146:149], v167 offset:16384
	ds_read_b128 v[150:153], v167 offset:18432
	ds_read_b128 v[154:157], v167 offset:20480
	ds_read_b128 v[158:161], v167 offset:22528
	v_lshl_add_u64 v[124:125], v[76:77], 0, s[40:41]
	v_lshl_add_u64 v[122:123], v[74:75], 0, s[40:41]
	v_lshl_add_u64 v[126:127], v[124:125], 0, s[74:75]
	s_add_i32 s10, s9, s5
	s_mov_b32 m0, s10
	s_nop 0
	global_load_lds_dwordx4 v[126:127], off
	v_lshl_add_u64 v[126:127], v[122:123], 0, s[94:95]
	s_add_i32 s11, s10, 0x400
	s_mov_b32 m0, s11
	s_nop 0
	global_load_lds_dwordx4 v[126:127], off
	v_lshl_add_u64 v[124:125], v[124:125], 0, s[76:77]
	s_add_i32 s11, s10, 0x800
	s_mov_b32 m0, s11
	s_nop 0
	global_load_lds_dwordx4 v[124:125], off
	v_lshl_add_u64 v[120:121], v[72:73], 0, s[40:41]
	v_lshl_add_u64 v[122:123], v[122:123], 0, s[54:55]
	s_addk_i32 s10, 0xc00
	s_mov_b32 m0, s10
	s_nop 0
	global_load_lds_dwordx4 v[122:123], off
	v_lshl_add_u64 v[118:119], v[70:71], 0, s[40:41]
	v_lshl_add_u64 v[128:129], v[120:121], 0, s[28:29]
	s_add_i32 s9, s9, s6
	s_mov_b32 m0, s9
	s_nop 0
	global_load_lds_dwordx4 v[128:129], off
	v_lshl_add_u64 v[122:123], v[118:119], 0, s[94:95]
	s_add_i32 s10, s9, 0x400
	s_mov_b32 m0, s10
	s_nop 0
	global_load_lds_dwordx4 v[122:123], off
	v_lshl_add_u64 v[120:121], v[120:121], 0, s[78:79]
	s_add_i32 s10, s9, 0x800
	s_mov_b32 m0, s10
	s_nop 0
	global_load_lds_dwordx4 v[120:121], off
	v_lshl_add_u64 v[118:119], v[118:119], 0, s[54:55]
	s_addk_i32 s9, 0xc00
	s_mov_b32 m0, s9
	s_nop 0
	global_load_lds_dwordx4 v[118:119], off
	s_mov_b32 s8, s7
	s_add_u32 s40, s40, 0x80
	s_addc_u32 s41, s41, 0
	s_cmpk_lg_i32 s40, 0x780
	s_waitcnt lgkmcnt(11)
	v_mfma_f32_16x16x32_bf16 v[62:65], v[102:105], v[86:89], v[62:65]
	v_mfma_f32_16x16x32_bf16 v[58:61], v[102:105], v[90:93], v[58:61]
	v_mfma_f32_16x16x32_bf16 v[54:57], v[102:105], v[94:97], v[54:57]
	v_mfma_f32_16x16x32_bf16 v[50:53], v[102:105], v[98:101], v[50:53]
	s_waitcnt lgkmcnt(10)
	v_mfma_f32_16x16x32_bf16 v[34:37], v[106:109], v[98:101], v[34:37]
	s_waitcnt lgkmcnt(9)
	v_mfma_f32_16x16x32_bf16 v[18:21], v[110:113], v[98:101], v[18:21]
	s_waitcnt lgkmcnt(8)
	v_mfma_f32_16x16x32_bf16 v[14:17], v[114:117], v[86:89], v[14:17]
	v_mfma_f32_16x16x32_bf16 v[10:13], v[114:117], v[90:93], v[10:13]
	v_mfma_f32_16x16x32_bf16 v[6:9], v[114:117], v[94:97], v[6:9]
	v_mfma_f32_16x16x32_bf16 v[2:5], v[114:117], v[98:101], v[2:5]
	v_mfma_f32_16x16x32_bf16 v[46:49], v[106:109], v[86:89], v[46:49]
	v_mfma_f32_16x16x32_bf16 v[42:45], v[106:109], v[90:93], v[42:45]
	v_mfma_f32_16x16x32_bf16 v[38:41], v[106:109], v[94:97], v[38:41]
	v_mfma_f32_16x16x32_bf16 v[30:33], v[110:113], v[86:89], v[30:33]
	v_mfma_f32_16x16x32_bf16 v[26:29], v[110:113], v[90:93], v[26:29]
	v_mfma_f32_16x16x32_bf16 v[22:25], v[110:113], v[94:97], v[22:25]
	s_waitcnt lgkmcnt(3)
	v_mfma_f32_16x16x32_bf16 v[62:65], v[146:149], v[130:133], v[62:65]
	v_mfma_f32_16x16x32_bf16 v[58:61], v[146:149], v[134:137], v[58:61]
	v_mfma_f32_16x16x32_bf16 v[54:57], v[146:149], v[138:141], v[54:57]
	v_mfma_f32_16x16x32_bf16 v[50:53], v[146:149], v[142:145], v[50:53]
	s_waitcnt lgkmcnt(2)
	v_mfma_f32_16x16x32_bf16 v[46:49], v[150:153], v[130:133], v[46:49]
	v_mfma_f32_16x16x32_bf16 v[42:45], v[150:153], v[134:137], v[42:45]
	v_mfma_f32_16x16x32_bf16 v[38:41], v[150:153], v[138:141], v[38:41]
	v_mfma_f32_16x16x32_bf16 v[34:37], v[150:153], v[142:145], v[34:37]
	s_waitcnt lgkmcnt(1)
	v_mfma_f32_16x16x32_bf16 v[30:33], v[154:157], v[130:133], v[30:33]
	v_mfma_f32_16x16x32_bf16 v[26:29], v[154:157], v[134:137], v[26:29]
	v_mfma_f32_16x16x32_bf16 v[22:25], v[154:157], v[138:141], v[22:25]
	v_mfma_f32_16x16x32_bf16 v[18:21], v[154:157], v[142:145], v[18:21]
	s_waitcnt lgkmcnt(0)
	v_mfma_f32_16x16x32_bf16 v[14:17], v[158:161], v[130:133], v[14:17]
	v_mfma_f32_16x16x32_bf16 v[10:13], v[158:161], v[134:137], v[10:13]
	v_mfma_f32_16x16x32_bf16 v[6:9], v[158:161], v[138:141], v[6:9]
	v_mfma_f32_16x16x32_bf16 v[2:5], v[158:161], v[142:145], v[2:5]
	s_cbranch_scc1 .LBB0_422
; DI int get_bid() { int b = blockIdx.x; asm volatile("" : "+s"(b)); return b; }
; DI float gelu_f(float x) { return 0.5f * x * (1.f + erff(x * 0.70710678118654752f)); }
; DI float silu_f(float x) { return x * __builtin_amdgcn_rcpf(1.f + __expf(-x)); }
; DI void phase_even(const Params& p, int e, int sub, char* smem) {
;     ...
;     for (int t = get_bid(); t < 132 * 40; t += gridDim.x) {
;       const int tm = t / 40, tn = t % 40;
;       const int t2 = t + gridDim.x, tm2 = t2 / 40, tn2 = t2 % 40;
;       const bool nx = t2 < 132 * 40;
;       gemm_tile<4>(hbuf + (size_t)tm * 128 * 1024, 1024, W + WE_IN + (size_t)tn * 128 * 1024, 1024, 1024, smem, tm * 128, tn * 128, epi, pre,
;                    nx ? hbuf + (size_t)tm2 * 128 * 1024 : nullptr, W + WE_IN + (size_t)tn2 * 128 * 1024);
;       pre = nx;
;     }
	v_mov_b32_e32 v170, 0x3f3504f3
	v_mov_b32_e32 v171, 0x3f3504f3
	v_mov_b32_e32 v172, 0xbfb8aa3b
	v_mov_b32_e32 v173, 0xbfb8aa3b
	v_mov_b32_e32 v174, 0x378e98ab
	v_mov_b32_e32 v175, 0x378e98ab
	v_mov_b32_e32 v176, 0xb9c68948
	v_mov_b32_e32 v177, 0xb9c68948
	v_mov_b32_e32 v178, 0x3b7cd369
	v_mov_b32_e32 v179, 0x3b7cd369
	v_mov_b32_e32 v180, 0xbcc618b2
	v_mov_b32_e32 v181, 0xbcc618b2
	v_mov_b32_e32 v186, 0x3dda74e4
	v_mov_b32_e32 v187, 0x3dda74e4
	v_mov_b32_e32 v188, 0x3f228afd
	v_mov_b32_e32 v189, 0x3f228afd
	v_mov_b32_e32 v190, 0x3e03c728
	v_mov_b32_e32 v191, 0x3e03c728
	v_mov_b32_e32 v192, 0xba1345e1
	v_mov_b32_e32 v193, 0xba1345e1
	v_mov_b32_e32 v194, 0x3ba10414
	v_mov_b32_e32 v195, 0x3ba10414
	v_mov_b32_e32 v196, 0xbcdac9b8
	v_mov_b32_e32 v197, 0xbcdac9b8
	v_mov_b32_e32 v224, 0x3de703be
	v_mov_b32_e32 v225, 0x3de703be
	v_mov_b32_e32 v226, 0xbec09330
	v_mov_b32_e32 v227, 0xbec09330
	v_mov_b32_e32 v228, 0x3e0375d0
	v_mov_b32_e32 v229, 0x3e0375d0
	v_mov_b32_e32 v230, 1.0
	v_mov_b32_e32 v231, 1.0
	v_mov_b32_e32 v232, 0.5
	v_mov_b32_e32 v233, 0.5
	v_mov_b32_e32 v234, -1.0
	v_mov_b32_e32 v235, -1.0
	v_readlane_b32 s8, v255, 5
	v_readlane_b32 s14, v255, 11
	s_add_i32 s4, s4, s14
	s_mul_hi_i32 s7, s4, 0x66666667
	s_lshr_b32 s8, s7, 31
	s_ashr_i32 s7, s7, 4
	s_add_i32 s46, s7, s8
	s_cmpk_gt_i32 s4, 0x149f
	v_readlane_b32 s9, v255, 6
	s_cselect_b64 s[44:45], -1, 0
	s_ashr_i32 s47, s46, 31
	s_lshl_b64 s[8:9], s[46:47], 18
	s_add_u32 s7, s0, s8
	s_addc_u32 s8, s1, s9
	s_cmpk_lt_i32 s4, 0x14a0
	s_waitcnt vmcnt(0)
	s_cselect_b32 s41, s8, 0
	s_cselect_b32 s40, s7, 0
	v_readlane_b32 s12, v255, 9
	v_readlane_b32 s13, v255, 10
	s_cmp_eq_u64 s[40:41], 0
	v_readlane_b32 s10, v255, 7
	v_readlane_b32 s11, v255, 8
	v_readlane_b32 s15, v255, 12
	s_barrier
	s_cbranch_scc1 .LBB0_425
	s_mul_i32 s7, s46, 40
	s_sub_i32 s8, s4, s7
	s_ashr_i32 s9, s8, 31
	s_lshl_b64 s[8:9], s[8:9], 18
	s_add_u32 s8, s12, s8
	s_addc_u32 s9, s13, s9
	v_lshl_add_u64 v[70:71], s[40:41], 0, v[68:69]
	v_lshl_add_u64 v[72:73], s[8:9], 0, v[66:67]
	v_lshl_add_u64 v[66:67], s[40:41], 0, v[66:67]
	s_mov_b32 m0, s5
	s_nop 0
	global_load_lds_dwordx4 v[70:71], off
	s_mov_b64 s[10:11], 0x4000
	v_lshl_add_u64 v[68:69], s[8:9], 0, v[68:69]
	v_lshl_add_u64 v[74:75], v[66:67], 0, s[10:11]
	s_add_i32 s7, s5, 0x400
	s_mov_b32 m0, s7
	s_nop 0
	global_load_lds_dwordx4 v[74:75], off
	s_mov_b64 s[12:13], 0x8000
	v_lshl_add_u64 v[70:71], v[70:71], 0, s[12:13]
	s_add_i32 s7, s5, 0x800
	s_mov_b32 m0, s7
	s_nop 0
	global_load_lds_dwordx4 v[70:71], off
	s_mov_b64 s[14:15], 0xc000
	v_lshl_add_u64 v[66:67], v[66:67], 0, s[14:15]
	s_add_i32 s7, s5, 0xc00
	s_mov_b32 m0, s7
	s_nop 0
	global_load_lds_dwordx4 v[66:67], off
	s_mov_b32 m0, s6
	s_nop 0
	global_load_lds_dwordx4 v[68:69], off
	v_lshl_add_u64 v[66:67], v[72:73], 0, s[10:11]
	s_add_i32 s6, s5, 0x4400
	s_mov_b32 m0, s6
	s_nop 0
	global_load_lds_dwordx4 v[66:67], off
	v_lshl_add_u64 v[66:67], v[68:69], 0, s[12:13]
	s_add_i32 s6, s5, 0x4800
	s_mov_b32 m0, s6
	s_nop 0
	global_load_lds_dwordx4 v[66:67], off
	v_lshl_add_u64 v[66:67], v[72:73], 0, s[14:15]
	s_addk_i32 s5, 0x4c00
	s_mov_b32 m0, s5
	s_nop 0
	global_load_lds_dwordx4 v[66:67], off

; DI int get_bid() { int b = blockIdx.x; asm volatile("" : "+s"(b)); return b; }
; template <int MT, class Epi>
; DI void gemm_tile(const u16* __restrict__ X, long ldx, const u16* __restrict__ W, long ldw, int K, char* smem,
;                   int m0, int n0, const Epi& epi, bool pre = false, const u16* Xn = nullptr, const u16* Wn = nullptr) {
;     ...
;   do {
;     asm volatile("s_waitcnt vmcnt(0)" ::: "memory");
;     __syncthreads();
;     if (kt + 1 < nk) GT_DMA((unsigned)((kt + 1) & 1) * 32768u)
;     else if (Xn != nullptr) { xe = Xn + oxe; xo = Xn + oxo; we = Wn + owe; wo = Wn + owo; GT_DMA(0u) }
;     const char* cur = smem + (kt & 1) * 32768;
; #pragma unroll
;     for (int ks = 0; ks < 2; ++ks) {
;       bf16x8 xf[MT], wf[4];
;       const int ch = ((ks * 4 + g) ^ rsw) << 4;
; #pragma unroll
;       for (int i = 0; i < MT; ++i) xf[i] = *(const bf16x8*)(cur + (wm * 16 * MT + i * 16 + lr) * 128 + ch);
; #pragma unroll
;       for (int i = 0; i < 4; ++i) wf[i] = *(const bf16x8*)(cur + 16384 + (wn * 64 + i * 16 + lr) * 128 + ch);
; #pragma unroll
;       for (int nt = 0; nt < 4; ++nt)
; #pragma unroll
;         for (int mt = 0; mt < MT; ++mt)
;           acc[nt][mt] = __builtin_amdgcn_mfma_f32_16x16x32_bf16(wf[nt], xf[mt], acc[nt][mt], 0, 0, 0);
;     }
;   } while (++kt < nk);
; DI void phase_odd(const Params& p, int o, int sub, char* smem) {
;     ...
;     for (int t = get_bid(); t < 132 * 14; t += gridDim.x) {
;       const int tm = t / 14, tn = t % 14;
;       const int t2 = t + gridDim.x, tm2 = t2 / 14, tn2 = t2 % 14;
;       const bool nx = t2 < 132 * 14;
;       gemm_tile<4>(hbuf + (size_t)tm * 128 * 1024, 1024, W + WO_IN + (size_t)tn * 128 * 1024, 1024, 1024, smem, tm * 128, tn * 128, epi, pre,
;                    nx ? hbuf + (size_t)tm2 * 128 * 1024 : nullptr, W + WO_IN + (size_t)tn2 * 128 * 1024);
;       pre = nx;
.LBB0_1026:
	s_add_i32 s7, s8, 0x8000
	s_and_b32 s9, s7, 0x8000
	s_waitcnt vmcnt(0)
	s_waitcnt lgkmcnt(0)
	s_barrier
	s_and_b32 s8, s8, 0x8000
	v_or_b32_e32 v162, s8, v84
	v_add3_u32 v163, v162, v80, v81
	v_add3_u32 v164, v162, v83, v81
	v_or_b32_e32 v165, s8, v82
	v_add3_u32 v166, v165, v80, v81
	v_add3_u32 v167, v165, v83, v81
	ds_read_b128 v[86:89], v163
	ds_read_b128 v[90:93], v163 offset:2048
	ds_read_b128 v[94:97], v163 offset:4096
	ds_read_b128 v[98:101], v163 offset:6144
	ds_read_b128 v[102:105], v164 offset:16384
	ds_read_b128 v[106:109], v164 offset:18432
	ds_read_b128 v[110:113], v164 offset:20480
	ds_read_b128 v[114:117], v164 offset:22528
	ds_read_b128 v[130:133], v166
	ds_read_b128 v[134:137], v166 offset:2048
	ds_read_b128 v[138:141], v166 offset:4096
	ds_read_b128 v[142:145], v166 offset:6144
	ds_read_b128 v[146:149], v167 offset:16384
	ds_read_b128 v[150:153], v167 offset:18432
	ds_read_b128 v[154:157], v167 offset:20480
	ds_read_b128 v[158:161], v167 offset:22528
	v_lshl_add_u64 v[124:125], v[74:75], 0, s[40:41]
	v_lshl_add_u64 v[122:123], v[72:73], 0, s[40:41]
	v_lshl_add_u64 v[126:127], v[124:125], 0, s[74:75]
	s_add_i32 s10, s9, s5
	s_mov_b32 m0, s10
	s_nop 0
	global_load_lds_dwordx4 v[126:127], off
	v_lshl_add_u64 v[126:127], v[122:123], 0, s[94:95]
	s_add_i32 s11, s10, 0x400
	s_mov_b32 m0, s11
	s_nop 0
	global_load_lds_dwordx4 v[126:127], off
	v_lshl_add_u64 v[124:125], v[124:125], 0, s[76:77]
	s_add_i32 s11, s10, 0x800
	s_mov_b32 m0, s11
	s_nop 0
	global_load_lds_dwordx4 v[124:125], off
	v_lshl_add_u64 v[120:121], v[70:71], 0, s[40:41]
	v_lshl_add_u64 v[122:123], v[122:123], 0, s[54:55]
	s_addk_i32 s10, 0xc00
	s_mov_b32 m0, s10
	s_nop 0
	global_load_lds_dwordx4 v[122:123], off
	v_lshl_add_u64 v[118:119], v[68:69], 0, s[40:41]
	v_lshl_add_u64 v[128:129], v[120:121], 0, s[28:29]
	s_add_i32 s9, s9, s6
	s_mov_b32 m0, s9
	s_nop 0
	global_load_lds_dwordx4 v[128:129], off
	v_lshl_add_u64 v[122:123], v[118:119], 0, s[94:95]
	s_add_i32 s10, s9, 0x400
	s_mov_b32 m0, s10
	s_nop 0
	global_load_lds_dwordx4 v[122:123], off
	v_lshl_add_u64 v[120:121], v[120:121], 0, s[78:79]
	s_add_i32 s10, s9, 0x800
	s_mov_b32 m0, s10
	s_nop 0
	global_load_lds_dwordx4 v[120:121], off
	v_lshl_add_u64 v[118:119], v[118:119], 0, s[54:55]
	s_addk_i32 s9, 0xc00
	s_mov_b32 m0, s9
	s_nop 0
	global_load_lds_dwordx4 v[118:119], off
	s_mov_b32 s8, s7
	s_add_u32 s40, s40, 0x80
	s_addc_u32 s41, s41, 0
	s_cmpk_lg_i32 s40, 0x780
	s_waitcnt lgkmcnt(11)
	v_mfma_f32_16x16x32_bf16 v[48:51], v[102:105], v[98:101], v[48:51]
	s_waitcnt lgkmcnt(10)
	v_mfma_f32_16x16x32_bf16 v[32:35], v[106:109], v[98:101], v[32:35]
	s_waitcnt lgkmcnt(9)
	v_mfma_f32_16x16x32_bf16 v[16:19], v[110:113], v[98:101], v[16:19]
	s_waitcnt lgkmcnt(8)
	v_mfma_f32_16x16x32_bf16 v[0:3], v[114:117], v[98:101], v[0:3]
	v_mfma_f32_16x16x32_bf16 v[60:63], v[102:105], v[86:89], v[60:63]
	v_mfma_f32_16x16x32_bf16 v[56:59], v[102:105], v[90:93], v[56:59]
	v_mfma_f32_16x16x32_bf16 v[52:55], v[102:105], v[94:97], v[52:55]
	v_mfma_f32_16x16x32_bf16 v[44:47], v[106:109], v[86:89], v[44:47]
	v_mfma_f32_16x16x32_bf16 v[40:43], v[106:109], v[90:93], v[40:43]
	v_mfma_f32_16x16x32_bf16 v[36:39], v[106:109], v[94:97], v[36:39]
	v_mfma_f32_16x16x32_bf16 v[28:31], v[110:113], v[86:89], v[28:31]
	v_mfma_f32_16x16x32_bf16 v[24:27], v[110:113], v[90:93], v[24:27]
	v_mfma_f32_16x16x32_bf16 v[20:23], v[110:113], v[94:97], v[20:23]
	v_mfma_f32_16x16x32_bf16 v[12:15], v[114:117], v[86:89], v[12:15]
	v_mfma_f32_16x16x32_bf16 v[8:11], v[114:117], v[90:93], v[8:11]
	v_mfma_f32_16x16x32_bf16 v[4:7], v[114:117], v[94:97], v[4:7]
	s_waitcnt lgkmcnt(3)
	v_mfma_f32_16x16x32_bf16 v[60:63], v[146:149], v[130:133], v[60:63]
	v_mfma_f32_16x16x32_bf16 v[56:59], v[146:149], v[134:137], v[56:59]
	v_mfma_f32_16x16x32_bf16 v[52:55], v[146:149], v[138:141], v[52:55]
	v_mfma_f32_16x16x32_bf16 v[48:51], v[146:149], v[142:145], v[48:51]
	s_waitcnt lgkmcnt(2)
	v_mfma_f32_16x16x32_bf16 v[44:47], v[150:153], v[130:133], v[44:47]
	v_mfma_f32_16x16x32_bf16 v[40:43], v[150:153], v[134:137], v[40:43]
	v_mfma_f32_16x16x32_bf16 v[36:39], v[150:153], v[138:141], v[36:39]
	v_mfma_f32_16x16x32_bf16 v[32:35], v[150:153], v[142:145], v[32:35]
	s_waitcnt lgkmcnt(1)
	v_mfma_f32_16x16x32_bf16 v[28:31], v[154:157], v[130:133], v[28:31]
	v_mfma_f32_16x16x32_bf16 v[24:27], v[154:157], v[134:137], v[24:27]
	v_mfma_f32_16x16x32_bf16 v[20:23], v[154:157], v[138:141], v[20:23]
	v_mfma_f32_16x16x32_bf16 v[16:19], v[154:157], v[142:145], v[16:19]
	s_waitcnt lgkmcnt(0)
	v_mfma_f32_16x16x32_bf16 v[12:15], v[158:161], v[130:133], v[12:15]
	v_mfma_f32_16x16x32_bf16 v[8:11], v[158:161], v[134:137], v[8:11]
	v_mfma_f32_16x16x32_bf16 v[4:7], v[158:161], v[138:141], v[4:7]
	v_mfma_f32_16x16x32_bf16 v[0:3], v[158:161], v[142:145], v[0:3]
	s_cbranch_scc1 .LBB0_1026
	v_readlane_b32 s8, v255, 5
	v_readlane_b32 s14, v255, 11
	s_add_i32 s4, s4, s14
	s_mul_hi_i32 s7, s4, 0x92492493
	s_add_i32 s7, s7, s4
	s_lshr_b32 s8, s7, 31
	s_ashr_i32 s7, s7, 3
	s_add_i32 s46, s7, s8
	s_cmpk_gt_i32 s4, 0x737
	v_readlane_b32 s9, v255, 6
	s_cselect_b64 s[40:41], -1, 0
	s_ashr_i32 s47, s46, 31
	s_lshl_b64 s[8:9], s[46:47], 18
	s_add_u32 s7, s0, s8
	s_addc_u32 s8, s1, s9
	s_cmpk_lt_i32 s4, 0x738
	s_waitcnt vmcnt(0)
	s_cselect_b32 s45, s8, 0
	s_cselect_b32 s44, s7, 0
	v_readlane_b32 s12, v255, 9
	v_readlane_b32 s13, v255, 10
	s_cmp_eq_u64 s[44:45], 0
	v_readlane_b32 s10, v255, 7
	v_readlane_b32 s11, v255, 8
	v_readlane_b32 s15, v255, 12
	s_barrier
	s_cbranch_scc1 .LBB0_1029
	s_mul_i32 s7, s46, 14
	s_sub_i32 s8, s4, s7
	s_ashr_i32 s9, s8, 31
	s_lshl_b64 s[8:9], s[8:9], 18
	s_add_u32 s8, s12, s8
	s_addc_u32 s9, s13, s9
	v_lshl_add_u64 v[68:69], s[44:45], 0, v[66:67]
	v_lshl_add_u64 v[70:71], s[8:9], 0, v[64:65]
	v_lshl_add_u64 v[64:65], s[44:45], 0, v[64:65]
	s_mov_b32 m0, s5
	s_nop 0
	global_load_lds_dwordx4 v[68:69], off
	s_mov_b64 s[10:11], 0x4000
	v_lshl_add_u64 v[66:67], s[8:9], 0, v[66:67]
	v_lshl_add_u64 v[72:73], v[64:65], 0, s[10:11]
	s_add_i32 s7, s5, 0x400
	s_mov_b32 m0, s7
	s_nop 0
	global_load_lds_dwordx4 v[72:73], off
	s_mov_b64 s[12:13], 0x8000
	v_lshl_add_u64 v[68:69], v[68:69], 0, s[12:13]
	s_add_i32 s7, s5, 0x800
	s_mov_b32 m0, s7
	s_nop 0
	global_load_lds_dwordx4 v[68:69], off
	s_mov_b64 s[14:15], 0xc000
	v_lshl_add_u64 v[64:65], v[64:65], 0, s[14:15]
	s_add_i32 s7, s5, 0xc00
	s_mov_b32 m0, s7
	s_nop 0
	global_load_lds_dwordx4 v[64:65], off
	s_mov_b32 m0, s6
	s_nop 0
	global_load_lds_dwordx4 v[66:67], off
	v_lshl_add_u64 v[64:65], v[70:71], 0, s[10:11]
	s_add_i32 s6, s5, 0x4400
	s_mov_b32 m0, s6
	s_nop 0
	global_load_lds_dwordx4 v[64:65], off
	v_lshl_add_u64 v[64:65], v[66:67], 0, s[12:13]
	s_add_i32 s6, s5, 0x4800
	s_mov_b32 m0, s6
	s_nop 0
	global_load_lds_dwordx4 v[64:65], off
	v_lshl_add_u64 v[64:65], v[70:71], 0, s[14:15]
	s_addk_i32 s5, 0x4c00
	s_mov_b32 m0, s5
	s_nop 0
	global_load_lds_dwordx4 v[64:65], off

; template <int MT, class Epi>
; DI void gemm_tile(const u16* __restrict__ X, long ldx, const u16* __restrict__ W, long ldw, int K, char* smem,
;                   int m0, int n0, const Epi& epi, bool pre = false, const u16* Xn = nullptr, const u16* Wn = nullptr) {
;     ...
;   do {
;     asm volatile("s_waitcnt vmcnt(0)" ::: "memory");
;     __syncthreads();
;     if (kt + 1 < nk) GT_DMA((unsigned)((kt + 1) & 1) * 32768u)
;     else if (Xn != nullptr) { xe = Xn + oxe; xo = Xn + oxo; we = Wn + owe; wo = Wn + owo; GT_DMA(0u) }
;     const char* cur = smem + (kt & 1) * 32768;
; #pragma unroll
;     for (int ks = 0; ks < 2; ++ks) {
;       bf16x8 xf[MT], wf[4];
;       const int ch = ((ks * 4 + g) ^ rsw) << 4;
; #pragma unroll
;       for (int i = 0; i < MT; ++i) xf[i] = *(const bf16x8*)(cur + (wm * 16 * MT + i * 16 + lr) * 128 + ch);
; #pragma unroll
;       for (int i = 0; i < 4; ++i) wf[i] = *(const bf16x8*)(cur + 16384 + (wn * 64 + i * 16 + lr) * 128 + ch);
; #pragma unroll
;       for (int nt = 0; nt < 4; ++nt)
; #pragma unroll
;         for (int mt = 0; mt < MT; ++mt)
;           acc[nt][mt] = __builtin_amdgcn_mfma_f32_16x16x32_bf16(wf[nt], xf[mt], acc[nt][mt], 0, 0, 0);
;     }
;   } while (++kt < nk);
.LBB0_1312:
	s_add_i32 s7, s8, 0x8000
	s_and_b32 s9, s7, 0x8000
	s_waitcnt vmcnt(0)
	s_waitcnt lgkmcnt(0)
	s_barrier
	s_and_b32 s8, s8, 0x8000
	v_or_b32_e32 v162, s8, v84
	v_add3_u32 v163, v162, v80, v81
	v_add3_u32 v164, v162, v83, v81
	v_or_b32_e32 v165, s8, v82
	v_add3_u32 v166, v165, v80, v81
	v_add3_u32 v167, v165, v83, v81
	ds_read_b128 v[86:89], v163
	ds_read_b128 v[90:93], v163 offset:2048
	ds_read_b128 v[94:97], v163 offset:4096
	ds_read_b128 v[98:101], v163 offset:6144
	ds_read_b128 v[102:105], v164 offset:16384
	ds_read_b128 v[106:109], v164 offset:18432
	ds_read_b128 v[110:113], v164 offset:20480
	ds_read_b128 v[114:117], v164 offset:22528
	ds_read_b128 v[130:133], v166
	ds_read_b128 v[134:137], v166 offset:2048
	ds_read_b128 v[138:141], v166 offset:4096
	ds_read_b128 v[142:145], v166 offset:6144
	ds_read_b128 v[146:149], v167 offset:16384
	ds_read_b128 v[150:153], v167 offset:18432
	ds_read_b128 v[154:157], v167 offset:20480
	ds_read_b128 v[158:161], v167 offset:22528
	v_lshl_add_u64 v[124:125], v[74:75], 0, s[40:41]
	v_lshl_add_u64 v[122:123], v[72:73], 0, s[40:41]
	v_lshl_add_u64 v[126:127], v[124:125], 0, s[74:75]
	s_add_i32 s10, s9, s5
	s_mov_b32 m0, s10
	s_nop 0
	global_load_lds_dwordx4 v[126:127], off
	v_lshl_add_u64 v[126:127], v[122:123], 0, s[94:95]
	s_add_i32 s11, s10, 0x400
	s_mov_b32 m0, s11
	s_nop 0
	global_load_lds_dwordx4 v[126:127], off
	v_lshl_add_u64 v[124:125], v[124:125], 0, s[76:77]
	s_add_i32 s11, s10, 0x800
	s_mov_b32 m0, s11
	s_nop 0
	global_load_lds_dwordx4 v[124:125], off
	v_lshl_add_u64 v[120:121], v[70:71], 0, s[40:41]
	v_lshl_add_u64 v[122:123], v[122:123], 0, s[54:55]
	s_addk_i32 s10, 0xc00
	s_mov_b32 m0, s10
	s_nop 0
	global_load_lds_dwordx4 v[122:123], off
	v_lshl_add_u64 v[118:119], v[68:69], 0, s[40:41]
	v_lshl_add_u64 v[128:129], v[120:121], 0, s[28:29]
	s_add_i32 s9, s9, s6
	s_mov_b32 m0, s9
	s_nop 0
	global_load_lds_dwordx4 v[128:129], off
	v_lshl_add_u64 v[122:123], v[118:119], 0, s[94:95]
	s_add_i32 s10, s9, 0x400
	s_mov_b32 m0, s10
	s_nop 0
	global_load_lds_dwordx4 v[122:123], off
	v_lshl_add_u64 v[120:121], v[120:121], 0, s[78:79]
	s_add_i32 s10, s9, 0x800
	s_mov_b32 m0, s10
	s_nop 0
	global_load_lds_dwordx4 v[120:121], off
	v_lshl_add_u64 v[118:119], v[118:119], 0, s[54:55]
	s_addk_i32 s9, 0xc00
	s_mov_b32 m0, s9
	s_nop 0
	global_load_lds_dwordx4 v[118:119], off
	s_mov_b32 s8, s7
	s_add_u32 s40, s40, 0x80
	s_addc_u32 s41, s41, 0
	s_cmpk_lg_i32 s40, 0x780
	s_waitcnt lgkmcnt(11)
	v_mfma_f32_16x16x32_bf16 v[48:51], v[102:105], v[98:101], v[48:51]
	s_waitcnt lgkmcnt(10)
	v_mfma_f32_16x16x32_bf16 v[32:35], v[106:109], v[98:101], v[32:35]
	s_waitcnt lgkmcnt(9)
	v_mfma_f32_16x16x32_bf16 v[16:19], v[110:113], v[98:101], v[16:19]
	s_waitcnt lgkmcnt(8)
	v_mfma_f32_16x16x32_bf16 v[0:3], v[114:117], v[98:101], v[0:3]
	v_mfma_f32_16x16x32_bf16 v[60:63], v[102:105], v[86:89], v[60:63]
	v_mfma_f32_16x16x32_bf16 v[56:59], v[102:105], v[90:93], v[56:59]
	v_mfma_f32_16x16x32_bf16 v[52:55], v[102:105], v[94:97], v[52:55]
	v_mfma_f32_16x16x32_bf16 v[44:47], v[106:109], v[86:89], v[44:47]
	v_mfma_f32_16x16x32_bf16 v[40:43], v[106:109], v[90:93], v[40:43]
	v_mfma_f32_16x16x32_bf16 v[36:39], v[106:109], v[94:97], v[36:39]
	v_mfma_f32_16x16x32_bf16 v[28:31], v[110:113], v[86:89], v[28:31]
	v_mfma_f32_16x16x32_bf16 v[24:27], v[110:113], v[90:93], v[24:27]
	v_mfma_f32_16x16x32_bf16 v[20:23], v[110:113], v[94:97], v[20:23]
	v_mfma_f32_16x16x32_bf16 v[12:15], v[114:117], v[86:89], v[12:15]
	v_mfma_f32_16x16x32_bf16 v[8:11], v[114:117], v[90:93], v[8:11]
	v_mfma_f32_16x16x32_bf16 v[4:7], v[114:117], v[94:97], v[4:7]
	s_waitcnt lgkmcnt(3)
	v_mfma_f32_16x16x32_bf16 v[60:63], v[146:149], v[130:133], v[60:63]
	v_mfma_f32_16x16x32_bf16 v[56:59], v[146:149], v[134:137], v[56:59]
	v_mfma_f32_16x16x32_bf16 v[52:55], v[146:149], v[138:141], v[52:55]
	v_mfma_f32_16x16x32_bf16 v[48:51], v[146:149], v[142:145], v[48:51]
	s_waitcnt lgkmcnt(2)
	v_mfma_f32_16x16x32_bf16 v[44:47], v[150:153], v[130:133], v[44:47]
	v_mfma_f32_16x16x32_bf16 v[40:43], v[150:153], v[134:137], v[40:43]
	v_mfma_f32_16x16x32_bf16 v[36:39], v[150:153], v[138:141], v[36:39]
	v_mfma_f32_16x16x32_bf16 v[32:35], v[150:153], v[142:145], v[32:35]
	s_waitcnt lgkmcnt(1)
	v_mfma_f32_16x16x32_bf16 v[28:31], v[154:157], v[130:133], v[28:31]
	v_mfma_f32_16x16x32_bf16 v[24:27], v[154:157], v[134:137], v[24:27]
	v_mfma_f32_16x16x32_bf16 v[20:23], v[154:157], v[138:141], v[20:23]
	v_mfma_f32_16x16x32_bf16 v[16:19], v[154:157], v[142:145], v[16:19]
	s_waitcnt lgkmcnt(0)
	v_mfma_f32_16x16x32_bf16 v[12:15], v[158:161], v[130:133], v[12:15]
	v_mfma_f32_16x16x32_bf16 v[8:11], v[158:161], v[134:137], v[8:11]
	v_mfma_f32_16x16x32_bf16 v[4:7], v[158:161], v[138:141], v[4:7]
	v_mfma_f32_16x16x32_bf16 v[0:3], v[158:161], v[142:145], v[0:3]
	s_cbranch_scc1 .LBB0_1312
; DI int get_bid() { int b = blockIdx.x; asm volatile("" : "+s"(b)); return b; }
; DI float gelu_f(float x) { return 0.5f * x * (1.f + erff(x * 0.70710678118654752f)); }
; DI float silu_f(float x) { return x * __builtin_amdgcn_rcpf(1.f + __expf(-x)); }
; DI void phase_even(const Params& p, int e, int sub, char* smem) {
;     ...
;     for (int t = get_bid(); t < 132 * 40; t += gridDim.x) {
;       const int tm = t / 40, tn = t % 40;
;       const int t2 = t + gridDim.x, tm2 = t2 / 40, tn2 = t2 % 40;
;       const bool nx = t2 < 132 * 40;
;       gemm_tile<4>(hbuf + (size_t)tm * 128 * 1024, 1024, W + WE_IN + (size_t)tn * 128 * 1024, 1024, 1024, smem, tm * 128, tn * 128, epi, pre,
;                    nx ? hbuf + (size_t)tm2 * 128 * 1024 : nullptr, W + WE_IN + (size_t)tn2 * 128 * 1024);
;       pre = nx;
;     }
	v_mov_b32_e32 v170, 0x3f3504f3
	v_mov_b32_e32 v171, 0x3f3504f3
	v_mov_b32_e32 v172, 0xbfb8aa3b
	v_mov_b32_e32 v173, 0xbfb8aa3b
	v_mov_b32_e32 v174, 0x378e98ab
	v_mov_b32_e32 v175, 0x378e98ab
	v_mov_b32_e32 v176, 0xb9c68948
	v_mov_b32_e32 v177, 0xb9c68948
	v_mov_b32_e32 v178, 0x3b7cd369
	v_mov_b32_e32 v179, 0x3b7cd369
	v_mov_b32_e32 v180, 0xbcc618b2
	v_mov_b32_e32 v181, 0xbcc618b2
	v_mov_b32_e32 v186, 0x3dda74e4
	v_mov_b32_e32 v187, 0x3dda74e4
	v_mov_b32_e32 v188, 0x3f228afd
	v_mov_b32_e32 v189, 0x3f228afd
	v_mov_b32_e32 v190, 0x3e03c728
	v_mov_b32_e32 v191, 0x3e03c728
	v_mov_b32_e32 v192, 0xba1345e1
	v_mov_b32_e32 v193, 0xba1345e1
	v_mov_b32_e32 v194, 0x3ba10414
	v_mov_b32_e32 v195, 0x3ba10414
	v_mov_b32_e32 v196, 0xbcdac9b8
	v_mov_b32_e32 v197, 0xbcdac9b8
	v_mov_b32_e32 v224, 0x3de703be
	v_mov_b32_e32 v225, 0x3de703be
	v_mov_b32_e32 v226, 0xbec09330
	v_mov_b32_e32 v227, 0xbec09330
	v_mov_b32_e32 v228, 0x3e0375d0
	v_mov_b32_e32 v229, 0x3e0375d0
	v_mov_b32_e32 v230, 1.0
	v_mov_b32_e32 v231, 1.0
	v_mov_b32_e32 v232, 0.5
	v_mov_b32_e32 v233, 0.5
	v_mov_b32_e32 v234, -1.0
	v_mov_b32_e32 v235, -1.0
	v_readlane_b32 s8, v255, 5
	v_readlane_b32 s14, v255, 11
	s_add_i32 s4, s4, s14
	s_mul_hi_i32 s7, s4, 0x66666667
	s_lshr_b32 s8, s7, 31
	s_ashr_i32 s7, s7, 4
	s_add_i32 s46, s7, s8
	s_cmpk_gt_i32 s4, 0x149f
	v_readlane_b32 s9, v255, 6
	s_cselect_b64 s[44:45], -1, 0
	s_ashr_i32 s47, s46, 31
	s_lshl_b64 s[8:9], s[46:47], 18
	s_add_u32 s7, s0, s8
	s_addc_u32 s8, s1, s9
	s_cmpk_lt_i32 s4, 0x14a0
	s_waitcnt vmcnt(0)
	s_cselect_b32 s41, s8, 0
	s_cselect_b32 s40, s7, 0
	v_readlane_b32 s12, v255, 9
	v_readlane_b32 s13, v255, 10
	s_cmp_eq_u64 s[40:41], 0
	v_readlane_b32 s10, v255, 7
	v_readlane_b32 s11, v255, 8
	v_readlane_b32 s15, v255, 12
	s_barrier
	s_cbranch_scc1 .LBB0_1315
	s_mul_i32 s7, s46, 40
	s_sub_i32 s8, s4, s7
	s_ashr_i32 s9, s8, 31
	s_lshl_b64 s[8:9], s[8:9], 18
	s_add_u32 s8, s12, s8
	s_addc_u32 s9, s13, s9
	v_lshl_add_u64 v[68:69], s[40:41], 0, v[66:67]
	v_lshl_add_u64 v[70:71], s[8:9], 0, v[64:65]
	v_lshl_add_u64 v[64:65], s[40:41], 0, v[64:65]
	s_mov_b32 m0, s5
	s_nop 0
	global_load_lds_dwordx4 v[68:69], off
	s_mov_b64 s[10:11], 0x4000
	v_lshl_add_u64 v[66:67], s[8:9], 0, v[66:67]
	v_lshl_add_u64 v[72:73], v[64:65], 0, s[10:11]
	s_add_i32 s7, s5, 0x400
	s_mov_b32 m0, s7
	s_nop 0
	global_load_lds_dwordx4 v[72:73], off
	s_mov_b64 s[12:13], 0x8000
	v_lshl_add_u64 v[68:69], v[68:69], 0, s[12:13]
	s_add_i32 s7, s5, 0x800
	s_mov_b32 m0, s7
	s_nop 0
	global_load_lds_dwordx4 v[68:69], off
	s_mov_b64 s[14:15], 0xc000
	v_lshl_add_u64 v[64:65], v[64:65], 0, s[14:15]
	s_add_i32 s7, s5, 0xc00
	s_mov_b32 m0, s7
	s_nop 0
	global_load_lds_dwordx4 v[64:65], off
	s_mov_b32 m0, s6
	s_nop 0
	global_load_lds_dwordx4 v[66:67], off
	v_lshl_add_u64 v[64:65], v[70:71], 0, s[10:11]
	s_add_i32 s6, s5, 0x4400
	s_mov_b32 m0, s6
	s_nop 0
	global_load_lds_dwordx4 v[64:65], off
	v_lshl_add_u64 v[64:65], v[66:67], 0, s[12:13]
	s_add_i32 s6, s5, 0x4800
	s_mov_b32 m0, s6
	s_nop 0
	global_load_lds_dwordx4 v[64:65], off
	v_lshl_add_u64 v[64:65], v[70:71], 0, s[14:15]
	s_addk_i32 s5, 0x4c00
	s_mov_b32 m0, s5
	s_nop 0
	global_load_lds_dwordx4 v[64:65], off
